# grid barrier poll loops: s_sleep removed between polls (local and cross-XCD generation polls)
# baseline (speedup 1.0000x reference)
.LBB0_42:
	s_and_b32 s12, s16, 0xff
	s_mov_b64 s[10:11], -1
	s_cmp_lg_u32 s12, 0
	s_mov_b64 s[14:15], -1
	s_nop 0
	s_cbranch_scc0 .LBB0_45
	s_and_b64 vcc, exec, s[14:15]
	s_cbranch_vccz .LBB0_41
